# attention: K frags preloaded w/ counted lgkmcnt, persistent -mrun C block, no half-step offset, one barrier per KV step
# speedup vs baseline: 1.0150x; 1.0150x over previous
.LBB0_734:
	s_waitcnt vmcnt(4)
	s_waitcnt lgkmcnt(0)
	s_barrier
	s_cmp_lt_i32 s43, 4
	s_branch .LBB0_736
	s_waitcnt lgkmcnt(0)
	s_barrier
.LBB0_736:
	v_mov_b32_e32 v14, v137
	v_mov_b32_e32 v15, v137
	s_addk_i32 s28, 0x100
	v_mul_u32_u24_e32 v147, 0xd0, v10
	v_mul_u32_u24_e32 v156, 0x90, v10
	v_lshlrev_b32_e32 v145, 2, v11
	v_mad_u64_u32 v[148:149], s[2:3], v140, 3, v[4:5]
	v_mad_u64_u32 v[150:151], s[2:3], v138, 3, v[2:3]
	v_mad_u64_u32 v[152:153], s[2:3], v136, 3, v[0:1]
	v_mov_b32_e32 v0, v137
	v_mov_b32_e32 v1, v137
	v_mov_b32_e32 v2, v137
	v_mov_b32_e32 v3, v137
	v_mov_b32_e32 v4, v137
	v_mov_b32_e32 v5, v137
	v_mov_b32_e32 v6, v137
	v_mov_b32_e32 v7, v137
	v_mov_b32_e32 v8, v137
	v_mov_b32_e32 v9, v137
	v_mov_b32_e32 v10, v137
	v_mov_b32_e32 v11, v137
	v_mov_b32_e32 v12, v137
	v_mov_b32_e32 v13, v137
	v_mov_b64_e32 v[30:31], v[14:15]
	s_lshr_b32 s46, s28, 6
	s_or_b32 s47, s44, 31
	s_mov_b32 s48, 0
	v_mov_b32_e32 v157, 0
	s_mov_b32 s49, 63
	v_mov_b64_e32 v[28:29], v[12:13]
	v_mov_b64_e32 v[26:27], v[10:11]
	v_mov_b64_e32 v[24:25], v[8:9]
	v_mov_b64_e32 v[22:23], v[6:7]
	v_mov_b64_e32 v[20:21], v[4:5]
	v_mov_b64_e32 v[18:19], v[2:3]
	v_mov_b64_e32 v[16:17], v[0:1]
	v_mov_b32_e32 v158, 0
	v_mov_b32_e32 v64, 0
	v_mov_b32_e32 v216, 0
	v_mov_b32_e32 v217, 0
	v_mov_b32_e32 v218, 0
	v_mov_b32_e32 v219, 0
	v_mov_b32_e32 v220, 0
	v_mov_b32_e32 v221, 0
	v_mov_b32_e32 v222, 0
	v_mov_b32_e32 v223, 0
	v_mov_b32_e32 v224, 0
	v_mov_b32_e32 v225, 0
	v_mov_b32_e32 v226, 0
	v_mov_b32_e32 v227, 0
	v_mov_b32_e32 v228, 0
	v_mov_b32_e32 v229, 0
	v_mov_b32_e32 v230, 0
	v_mov_b32_e32 v231, 0
	s_waitcnt vmcnt(0)
	s_branch .LBB0_740
.LBB0_737:
	v_add_f32_e32 v157, v157, v66
	v_xor_b32_e32 v64, 0x80000000, v157
	v_mov_b32_e32 v216, v64
	v_mov_b32_e32 v217, v64
	v_mov_b32_e32 v218, v64
	v_mov_b32_e32 v219, v64
	v_mov_b32_e32 v220, v64
	v_mov_b32_e32 v221, v64
	v_mov_b32_e32 v222, v64
	v_mov_b32_e32 v223, v64
	v_mov_b32_e32 v224, v64
	v_mov_b32_e32 v225, v64
	v_mov_b32_e32 v226, v64
	v_mov_b32_e32 v227, v64
	v_mov_b32_e32 v228, v64
	v_mov_b32_e32 v229, v64
	v_mov_b32_e32 v230, v64
	v_mov_b32_e32 v231, v64
	v_pk_add_f32 v[32:33], v[32:33], v[66:67] op_sel_hi:[1,0] neg_lo:[0,1] neg_hi:[0,1]
	v_pk_add_f32 v[48:49], v[48:49], v[66:67] op_sel_hi:[1,0] neg_lo:[0,1] neg_hi:[0,1]
	v_pk_add_f32 v[34:35], v[34:35], v[66:67] op_sel_hi:[1,0] neg_lo:[0,1] neg_hi:[0,1]
	v_pk_add_f32 v[50:51], v[50:51], v[66:67] op_sel_hi:[1,0] neg_lo:[0,1] neg_hi:[0,1]
	v_pk_add_f32 v[36:37], v[36:37], v[66:67] op_sel_hi:[1,0] neg_lo:[0,1] neg_hi:[0,1]
	v_pk_add_f32 v[52:53], v[52:53], v[66:67] op_sel_hi:[1,0] neg_lo:[0,1] neg_hi:[0,1]
	v_pk_add_f32 v[38:39], v[38:39], v[66:67] op_sel_hi:[1,0] neg_lo:[0,1] neg_hi:[0,1]
	v_pk_add_f32 v[54:55], v[54:55], v[66:67] op_sel_hi:[1,0] neg_lo:[0,1] neg_hi:[0,1]
	v_pk_add_f32 v[40:41], v[40:41], v[66:67] op_sel_hi:[1,0] neg_lo:[0,1] neg_hi:[0,1]
	v_pk_add_f32 v[56:57], v[56:57], v[66:67] op_sel_hi:[1,0] neg_lo:[0,1] neg_hi:[0,1]
	v_pk_add_f32 v[42:43], v[42:43], v[66:67] op_sel_hi:[1,0] neg_lo:[0,1] neg_hi:[0,1]
	v_pk_add_f32 v[58:59], v[58:59], v[66:67] op_sel_hi:[1,0] neg_lo:[0,1] neg_hi:[0,1]
	v_pk_add_f32 v[44:45], v[44:45], v[66:67] op_sel_hi:[1,0] neg_lo:[0,1] neg_hi:[0,1]
	v_pk_add_f32 v[60:61], v[60:61], v[66:67] op_sel_hi:[1,0] neg_lo:[0,1] neg_hi:[0,1]
	v_pk_add_f32 v[46:47], v[46:47], v[66:67] op_sel_hi:[1,0] neg_lo:[0,1] neg_hi:[0,1]
	v_pk_add_f32 v[62:63], v[62:63], v[66:67] op_sel_hi:[1,0] neg_lo:[0,1] neg_hi:[0,1]

.LBB0_739:
	s_waitcnt lgkmcnt(0)
	s_add_i32 s48, s48, 1
	s_add_i32 s49, s49, 64
	v_lshl_add_u64 v[148:149], v[148:149], 0, v[140:141]
	v_lshl_add_u64 v[150:151], v[150:151], 0, v[138:139]
	s_cmp_ge_u32 s48, s46
	v_lshl_add_u64 v[152:153], v[152:153], 0, v[136:137]
	s_cbranch_scc1 .LBB0_759

.LBB0_743:
	s_sub_i32 s26, s49, 63
	s_cmp_le_i32 s26, s47
	s_cselect_b64 s[28:29], -1, 0
	s_cmp_gt_i32 s26, s47
	s_cbranch_scc1 .LBB0_756
	s_and_b32 s26, s48, 3
	s_mulk_i32 s26, 0x5800
	s_add_i32 s26, s26, 0
	v_add3_u32 v159, s26, v147, v146
	v_add3_u32 v232, s26, v156, v146
	ds_read_b128 v[168:171], v159
	ds_read_b128 v[192:195], v159 offset:6656
	ds_read_b128 v[172:175], v159 offset:32
	ds_read_b128 v[196:199], v159 offset:6688
	ds_read_b128 v[176:179], v159 offset:64
	ds_read_b128 v[200:203], v159 offset:6720
	ds_read_b128 v[180:183], v159 offset:96
	ds_read_b128 v[204:207], v159 offset:6752
	ds_read_b128 v[184:187], v159 offset:128
	ds_read_b128 v[208:211], v159 offset:6784
	ds_read_b128 v[188:191], v159 offset:160
	ds_read_b128 v[212:215], v159 offset:6816
	s_waitcnt lgkmcnt(10)
	v_mfma_f32_32x32x16_bf16 v[32:47], v[168:171], v[96:99], v[216:231]
	v_mfma_f32_32x32x16_bf16 v[48:63], v[192:195], v[96:99], v[216:231]
	ds_read_b128 v[108:111], v232 offset:13312
	ds_read_b128 v[124:127], v232 offset:17920
	s_waitcnt lgkmcnt(10)
	v_mfma_f32_32x32x16_bf16 v[32:47], v[172:175], v[80:83], v[32:47]
	v_mfma_f32_32x32x16_bf16 v[48:63], v[196:199], v[80:83], v[48:63]
	ds_read_b128 v[104:107], v232 offset:13344
	ds_read_b128 v[120:123], v232 offset:17952
	s_waitcnt lgkmcnt(10)
	v_mfma_f32_32x32x16_bf16 v[32:47], v[176:179], v[84:87], v[32:47]
	v_mfma_f32_32x32x16_bf16 v[48:63], v[200:203], v[84:87], v[48:63]
	ds_read_b128 v[112:115], v232 offset:13376
	ds_read_b128 v[132:135], v232 offset:17984
	s_waitcnt lgkmcnt(10)
	v_mfma_f32_32x32x16_bf16 v[32:47], v[180:183], v[88:91], v[32:47]
	v_mfma_f32_32x32x16_bf16 v[48:63], v[204:207], v[88:91], v[48:63]
	ds_read_b128 v[116:119], v232 offset:13408
	ds_read_b128 v[128:131], v232 offset:18016
	s_waitcnt lgkmcnt(10)
	v_mfma_f32_32x32x16_bf16 v[32:47], v[184:187], v[92:95], v[32:47]
	v_mfma_f32_32x32x16_bf16 v[48:63], v[208:211], v[92:95], v[48:63]
	s_waitcnt lgkmcnt(8)
	v_mfma_f32_32x32x16_bf16 v[32:47], v[188:191], v[100:103], v[32:47]
	v_mfma_f32_32x32x16_bf16 v[48:63], v[212:215], v[100:103], v[48:63]
	s_mov_b64 s[26:27], -1
	s_and_b64 vcc, exec, s[2:3]
	s_cbranch_vccnz .LBB0_757

.LBB0_759:
	s_cmp_lt_i32 s43, 4
	s_branch .LBB0_697
	s_waitcnt lgkmcnt(0)
	s_barrier
	s_branch .LBB0_697
